# ktab table: lane-parallel pre-pass for the lane-uniform transcendental part, loop reads it via readlane
# speedup vs baseline: 1.0018x; 1.0018x over previous
; DI float2 cpowe(const S5c& c, float e) { const float mg = __expf(e * c.a); float s, co; sincos_rev(e * c.b * 0.15915494309189535f, s, co); return make_float2(mg * co, mg * s); }
; DI float2 cmul(float2 x, float2 y) { return make_float2(x.x * y.x - x.y * y.y, x.x * y.y + x.y * y.x); }
; DI void phase_prep(const Params& P, int layer, int gtid, int nthr) {
;     ...
;     for (int idx = gtid; idx < S5G * 2 * 4 * 256; idx += nthr) {
;         const int q = idx & 15, p = (idx >> 4) & 15, kb = (idx >> 8) & 3, d = (idx >> 10) & 1, g = idx >> 11;
;         const int ig = (layer * 2 + d) * S5G + g; float acc[8];
; #pragma unroll
;         for (int k = 0; k < 8; ++k) acc[k] = 0.f;
;         for (int n = 0; n < 64; ++n) {
;             const S5c c = s5_load(ldt, lre, lim, layer, d, g, n);
;             const float2 bb = cmul(s5_coef(c), make_float2(bre[((size_t)ig * 64 + n) * 16 + q], bim[((size_t)ig * 64 + n) * 16 + q]));
;             const float2 cc = make_float2(cre[((size_t)ig * 16 + p) * 64 + n], cim[((size_t)ig * 16 + p) * 64 + n]);
;             float2 w = cmul(cmul(cc, bb), cpowe(c, (float)(8 * kb)));
;             const float2 l1 = cpowe(c, 1.0f);
; #pragma unroll
;             for (int k = 0; k < 8; ++k) { acc[k] += w.x; w = cmul(w, l1); }
.LBB0_322:
	v_bfe_u32 v29, v28, 10, 1
	v_or_b32_e32 v8, s16, v29
	v_ashrrev_i32_e32 v30, 11, v28
	v_mad_u32_u24 v12, v8, 24, v30
	v_ashrrev_i32_e32 v13, 31, v12
	v_lshl_add_u64 v[8:9], v[12:13], 2, s[24:25]
	global_load_dword v33, v[8:9], off
	v_lshlrev_b32_e32 v14, 6, v12
	v_lshlrev_b32_e32 v16, 2, v3
	v_lshlrev_b64 v[12:13], 12, v[12:13]
	v_ashrrev_i32_e32 v15, 31, v14
	s_movk_i32 s2, 0xf00
	v_and_or_b32 v22, v16, s2, v12
	v_mov_b32_e32 v23, v13
	v_lshl_add_u64 v[16:17], v[4:5], 0, v[12:13]
	v_lshl_add_u64 v[18:19], v[6:7], 0, v[12:13]
	v_lshlrev_b64 v[12:13], 2, v[14:15]
	v_lshl_add_u64 v[24:25], s[20:21], 0, v[12:13]
	v_lshl_add_u64 v[26:27], s[22:23], 0, v[12:13]
	v_lshrrev_b32_e32 v9, 5, v28
	v_mov_b32_e32 v8, 0
	v_and_b32_e32 v31, 24, v9
	s_mov_b64 s[8:9], 0
	v_mov_b32_e32 v9, v8
	v_mov_b32_e32 v10, v8
	v_mov_b32_e32 v11, v8
	v_cvt_f32_ubyte0_e32 v32, v31
	v_lshl_add_u64 v[20:21], s[42:43], 0, v[22:23]
	v_lshl_add_u64 v[22:23], s[46:47], 0, v[22:23]
	v_mov_b32_e32 v13, v8
	v_mov_b32_e32 v14, v8
	v_mov_b32_e32 v15, v8
	s_mov_b32 s2, 0x3da2f983
	s_waitcnt vmcnt(0)
	v_mul_f32_e32 v12, 0x3fb8aa3b, v33
	v_exp_f32_e32 v33, v12
	v_mov_b32_e32 v12, v8
	v_lshlrev_b32_e32 v34, 2, v233
	v_mov_b32_e32 v35, 0
	v_lshl_add_u64 v[36:37], v[26:27], 0, v[34:35]
	v_lshl_add_u64 v[34:35], v[24:25], 0, v[34:35]
	global_load_dword v37, v[36:37], off
	global_load_dword v36, v[34:35], off
	s_waitcnt vmcnt(0)
	v_mul_f32_e32 v39, v33, v37
	v_mul_f32_e32 v35, v33, v36
	v_pk_mul_f32 v[44:45], v[36:37], v[36:37]
	v_mov_b32_e32 v46, v37
	v_mul_f32_e32 v37, 0x3fb8aa3b, v35
	v_mul_f32_e32 v41, 0.15915494, v39
	v_mul_f32_e32 v43, 0x3da2f983, v39
	v_exp_f32_e32 v48, v37
	v_floor_f32_e32 v37, v41
	v_floor_f32_e32 v41, v43
	v_mul_f32_e32 v35, v35, v32
	v_mul_f32_e32 v47, v39, v32
	v_fma_f32 v37, v39, 0.15915494, -v37
	v_fma_f32 v39, v39, s2, -v41
	v_mul_f32_e32 v35, 0x3fb8aa3b, v35
	v_mul_f32_e32 v43, 0.15915494, v47
	v_sin_f32_e32 v53, v37
	v_cos_f32_e32 v54, v37
	v_sin_f32_e32 v37, v39
	v_exp_f32_e32 v50, v35
	v_floor_f32_e32 v35, v43
	v_fma_f32 v35, v47, 0.15915494, -v35
	v_sin_f32_e32 v57, v35
	v_cos_f32_e32 v56, v35
	v_add_f32_e32 v35, -1.0, v48
	v_mul_f32_e32 v37, v37, v37
	v_add_f32_e32 v59, 1.0, v35
	v_mul_f32_e32 v58, v35, v54
	v_mov_b32_e32 v55, v53
	v_add_f32_e32 v52, v37, v37
	v_pk_mul_f32 v[48:49], v[48:49], v[54:55] op_sel_hi:[0,1]
	v_pk_add_f32 v[54:55], v[58:59], v[52:53] neg_lo:[0,1] neg_hi:[0,1]
	v_pk_mul_f32 v[52:53], v[58:59], v[52:53]
	v_pk_mul_f32 v[50:51], v[50:51], v[56:57] op_sel_hi:[0,1]
	v_mov_b32_e32 v57, v53
	v_pk_mov_b32 v[52:53], v[52:53], v[54:55] op_sel:[1,0]
	v_mov_b32_e32 v56, v54
	v_pk_mul_f32 v[46:47], v[46:47], v[52:53] op_sel_hi:[0,1]
	v_pk_add_f32 v[44:45], v[44:45], v[44:45] op_sel:[0,1] op_sel_hi:[0,1]
	v_pk_fma_f32 v[52:53], v[36:37], v[54:55], v[46:47]
	v_pk_fma_f32 v[36:37], v[36:37], v[56:57], v[46:47] op_sel_hi:[0,1,1] neg_lo:[0,0,1] neg_hi:[0,0,1]
	v_div_scale_f32 v35, s[10:11], v45, v45, v37
	v_div_scale_f32 v39, s[10:11], v44, v44, v52
	v_rcp_f32_e32 v43, v35
	v_rcp_f32_e32 v46, v39
	v_div_scale_f32 v36, vcc, v37, v45, v37
	v_fma_f32 v47, -v35, v43, 1.0
	v_fma_f32 v53, -v39, v46, 1.0
	v_fmac_f32_e32 v43, v47, v43
	v_div_scale_f32 v41, s[10:11], v52, v44, v52
	v_fmac_f32_e32 v46, v53, v46
	v_mul_f32_e32 v47, v36, v43
	v_mul_f32_e32 v53, v41, v46
	v_fma_f32 v54, -v35, v47, v36
	v_fma_f32 v55, -v39, v53, v41
	v_fmac_f32_e32 v47, v54, v43
	v_fmac_f32_e32 v53, v55, v46
	v_fma_f32 v35, -v35, v47, v36
	v_fma_f32 v36, -v39, v53, v41
	v_div_fmas_f32 v35, v35, v43, v47
	s_mov_b64 vcc, s[10:11]
	v_div_fixup_f32 v37, v35, v45, v37
	v_div_fmas_f32 v35, v36, v46, v53
	v_div_fixup_f32 v36, v35, v44, v52
	v_mov_b32_e32 v60, v36
	v_mov_b32_e32 v61, v37
	v_mov_b32_e32 v62, v48
	v_mov_b32_e32 v63, v49
	v_mov_b32_e32 v64, v50
	v_mov_b32_e32 v65, v51
; DI float2 cpowe(const S5c& c, float e) { const float mg = __expf(e * c.a); float s, co; sincos_rev(e * c.b * 0.15915494309189535f, s, co); return make_float2(mg * co, mg * s); }
; DI float2 cmul(float2 x, float2 y) { return make_float2(x.x * y.x - x.y * y.y, x.x * y.y + x.y * y.x); }
; DI void phase_prep(const Params& P, int layer, int gtid, int nthr) {
;     ...
;         for (int n = 0; n < 64; ++n) {
;             const S5c c = s5_load(ldt, lre, lim, layer, d, g, n);
;             const float2 bb = cmul(s5_coef(c), make_float2(bre[((size_t)ig * 64 + n) * 16 + q], bim[((size_t)ig * 64 + n) * 16 + q]));
;             const float2 cc = make_float2(cre[((size_t)ig * 16 + p) * 64 + n], cim[((size_t)ig * 16 + p) * 64 + n]);
;             float2 w = cmul(cmul(cc, bb), cpowe(c, (float)(8 * kb)));
;             const float2 l1 = cpowe(c, 1.0f);
; #pragma unroll
;             for (int k = 0; k < 8; ++k) { acc[k] += w.x; w = cmul(w, l1); }
;         }
; #pragma unroll
;         for (int k = 0; k < 8; ++k) ktab[((((g * 2 + d) * 32 + 8 * kb + k) * 16 + p) * 16) + q] = acc[k];
;     }
.LBB0_323:
	global_load_dword v38, v[16:17], off
	global_load_dword v40, v[18:19], off
	s_nop 0
	s_nop 0
	v_lshl_add_u64 v[42:43], v[20:21], 0, s[8:9]
	v_lshl_add_u64 v[34:35], v[22:23], 0, s[8:9]
	global_load_dword v42, v[42:43], off
	s_nop 0
	global_load_dword v34, v[34:35], off
	s_add_u32 s8, s8, 4
	s_addc_u32 s9, s9, 0
	s_lshr_b32 s10, s8, 2
	s_sub_u32 s10, s10, 1
	v_lshl_add_u64 v[16:17], v[16:17], 0, 64
	v_lshl_add_u64 v[18:19], v[18:19], 0, 64
	s_cmpk_eq_i32 s8, 0x100
	s_nop 0
	v_readlane_b32 s11, v60, s10
	v_readlane_b32 s100, v61, s10
	v_readlane_b32 s101, v62, s10
	v_readlane_b32 vcc_lo, v63, s10
	v_readlane_b32 vcc_hi, v64, s10
	v_readlane_b32 s2, v65, s10
	s_nop 1
	v_mov_b32_e32 v36, s11
	v_mov_b32_e32 v37, s100
	v_mov_b32_e32 v48, s101
	v_mov_b32_e32 v49, vcc_lo
	v_mov_b32_e32 v50, vcc_hi
	v_mov_b32_e32 v51, s2
	s_waitcnt vmcnt(2)
	v_pk_mul_f32 v[40:41], v[40:41], v[36:37] op_sel:[0,1] op_sel_hi:[0,0]
	v_pk_fma_f32 v[44:45], v[38:39], v[36:37], v[40:41] op_sel_hi:[0,1,1] neg_lo:[0,0,1] neg_hi:[0,0,1]
	v_pk_fma_f32 v[36:37], v[38:39], v[36:37], v[40:41] op_sel_hi:[0,1,1]
	v_mov_b32_e32 v39, v37
	v_pk_mov_b32 v[36:37], v[36:37], v[44:45] op_sel:[1,0]
	v_mov_b32_e32 v38, v44
	s_waitcnt vmcnt(0)
	v_pk_mul_f32 v[34:35], v[34:35], v[36:37] op_sel_hi:[0,1]
	v_pk_fma_f32 v[36:37], v[42:43], v[44:45], v[34:35] neg_lo:[0,0,1] neg_hi:[0,0,1]
	v_pk_fma_f32 v[34:35], v[42:43], v[38:39], v[34:35] op_sel_hi:[0,1,1]
	v_mov_b32_e32 v37, v35
	v_mul_f32_e32 v34, v51, v35
	v_pk_mul_f32 v[38:39], v[50:51], v[36:37] op_sel:[1,0] op_sel_hi:[0,1]
	v_pk_fma_f32 v[34:35], v[50:51], v[36:37], v[34:35] op_sel_hi:[1,1,0] neg_lo:[0,0,1] neg_hi:[0,0,1]
	v_pk_add_f32 v[36:37], v[38:39], v[38:39] op_sel:[0,1] op_sel_hi:[0,1]
	v_pk_mul_f32 v[36:37], v[48:49], v[36:37] op_sel:[1,0] op_sel_hi:[0,1]
	v_mov_b32_e32 v39, v34
	v_pk_fma_f32 v[40:41], v[48:49], v[34:35], v[36:37] op_sel_hi:[1,0,1] neg_lo:[0,0,1] neg_hi:[0,0,1]
	v_pk_fma_f32 v[34:35], v[48:49], v[34:35], v[36:37] op_sel_hi:[1,0,1]
	v_mov_b32_e32 v38, v40
	v_mov_b32_e32 v41, v35
	v_pk_mul_f32 v[36:37], v[48:49], v[40:41] op_sel:[1,0] op_sel_hi:[0,1]
	v_mul_f32_e32 v34, v49, v35
	v_pk_add_f32 v[36:37], v[36:37], v[36:37] op_sel:[0,1] op_sel_hi:[0,1]
	v_pk_fma_f32 v[34:35], v[48:49], v[40:41], v[34:35] op_sel_hi:[1,1,0] neg_lo:[0,0,1] neg_hi:[0,0,1]
	v_pk_mul_f32 v[36:37], v[48:49], v[36:37] op_sel:[1,0] op_sel_hi:[0,1]
	v_pk_add_f32 v[14:15], v[14:15], v[38:39]
	v_mov_b32_e32 v39, v34
	v_pk_fma_f32 v[40:41], v[48:49], v[34:35], v[36:37] op_sel_hi:[1,0,1] neg_lo:[0,0,1] neg_hi:[0,0,1]
	v_pk_fma_f32 v[34:35], v[48:49], v[34:35], v[36:37] op_sel_hi:[1,0,1]
	v_mov_b32_e32 v38, v40
	v_mov_b32_e32 v41, v35
	v_pk_mul_f32 v[36:37], v[48:49], v[40:41] op_sel:[1,0] op_sel_hi:[0,1]
	v_mul_f32_e32 v34, v49, v35
	v_pk_add_f32 v[36:37], v[36:37], v[36:37] op_sel:[0,1] op_sel_hi:[0,1]
	v_pk_fma_f32 v[34:35], v[48:49], v[40:41], v[34:35] op_sel_hi:[1,1,0] neg_lo:[0,0,1] neg_hi:[0,0,1]
	v_pk_mul_f32 v[36:37], v[48:49], v[36:37] op_sel:[1,0] op_sel_hi:[0,1]
	v_pk_add_f32 v[12:13], v[12:13], v[38:39]
	v_mov_b32_e32 v39, v34
	v_pk_fma_f32 v[40:41], v[48:49], v[34:35], v[36:37] op_sel_hi:[1,0,1] neg_lo:[0,0,1] neg_hi:[0,0,1]
	v_pk_fma_f32 v[34:35], v[48:49], v[34:35], v[36:37] op_sel_hi:[1,0,1]
	v_mov_b32_e32 v38, v40
	v_mov_b32_e32 v41, v35
	v_mul_f32_e32 v34, v49, v40
	v_mul_f32_e32 v36, v49, v35
	v_pk_fma_f32 v[34:35], v[48:49], v[40:41], v[34:35] op_sel:[1,0,0] op_sel_hi:[0,1,0]
	v_pk_fma_f32 v[36:37], v[48:49], v[40:41], v[36:37] op_sel_hi:[1,1,0] neg_lo:[0,0,1] neg_hi:[0,0,1]
	v_mul_f32_e32 v34, v49, v35
	v_mov_b32_e32 v37, v35
	v_pk_fma_f32 v[34:35], v[48:49], v[36:37], v[34:35] op_sel_hi:[1,1,0] neg_lo:[0,0,1] neg_hi:[0,0,1]
	v_pk_add_f32 v[10:11], v[10:11], v[38:39]
	v_mov_b32_e32 v35, v36
	v_pk_add_f32 v[8:9], v[8:9], v[34:35]
	s_cbranch_scc0 .LBB0_323
	v_lshlrev_b32_e32 v16, 6, v30
	v_lshlrev_b32_e32 v17, 5, v29
	v_or3_b32 v16, v17, v16, v31
	v_lshl_or_b32 v16, v16, 8, v1
	v_ashrrev_i32_e32 v17, 31, v16
	v_lshl_add_u64 v[16:17], v[16:17], 2, s[12:13]
	global_store_dword v[16:17], v15, off
	global_store_dword v[16:17], v14, off offset:1024
	global_store_dword v[16:17], v13, off offset:2048
	global_store_dword v[16:17], v12, off offset:3072
	v_add_co_u32_e32 v12, vcc, 0x1000, v16
	v_add_u32_e32 v28, s84, v28
	s_nop 0
	v_addc_co_u32_e32 v13, vcc, 0, v17, vcc
	s_mov_b32 s2, 0xbfff
	v_cmp_lt_i32_e32 vcc, s2, v28
	s_or_b64 s[14:15], vcc, s[14:15]
	v_add_u32_e32 v3, s0, v3
	global_store_dword v[12:13], v11, off
	global_store_dword v[12:13], v10, off offset:1024
	global_store_dword v[12:13], v9, off offset:2048
	global_store_dword v[12:13], v8, off offset:3072
	s_andn2_b64 exec, exec, s[14:15]
	s_cbranch_execnz .LBB0_322
